# hoisted the serialized residual-epilogue and final-norm row loads above their waits with counted vmcnt, on top of default-policy weight-copy stores
# speedup vs baseline: 1.0040x; 1.0040x over previous
.LBB0_835:
	v_and_b32_e32 v153, 64, v208
	v_xor_b32_e32 v152, 16, v208
	v_add_u32_e32 v154, 64, v153
	v_cmp_lt_i32_e32 vcc, v152, v154
	v_lshl_add_u32 v151, s6, 8, v146
	v_lshl_or_b32 v2, s17, 9, v149
	v_readlane_b32 s2, v254, 39
	v_cndmask_b32_e32 v152, v208, v152, vcc
	v_lshl_add_u32 v2, v151, 12, v2
	v_readlane_b32 s3, v254, 40
	v_lshlrev_b32_e32 v153, 2, v152
	v_xor_b32_e32 v152, 32, v208
	v_cmp_lt_i32_e32 vcc, v152, v154
	s_nop 1
	global_load_dwordx4 v[154:157], v2, s[2:3]
	global_load_dwordx4 v[158:161], v2, s[2:3] offset:256
	v_lshl_add_u64 v[144:145], s[2:3], 0, v[2:3]
	v_cndmask_b32_e32 v152, v208, v152, vcc
	v_lshlrev_b32_e32 v152, 2, v152
	s_mov_b32 s99, 0
	s_mov_b32 s98, 0x10000
	v_lshl_add_u64 v[228:229], v[144:145], 0, s[98:99]
	global_load_dwordx4 v[168:171], v[228:229], off offset:256
	global_load_dwordx4 v[172:175], v[228:229], off
	s_mov_b32 s98, 0x20000
	v_lshl_add_u64 v[230:231], v[144:145], 0, s[98:99]
	global_load_dwordx4 v[176:179], v[230:231], off offset:256
	global_load_dwordx4 v[180:183], v[230:231], off
	s_mov_b32 s98, 0x30000
	v_lshl_add_u64 v[232:233], v[144:145], 0, s[98:99]
	global_load_dwordx4 v[184:187], v[232:233], off offset:256
	global_load_dwordx4 v[188:191], v[232:233], off
	s_mov_b32 s98, 0x80000
	v_lshl_add_u64 v[234:235], v[144:145], 0, s[98:99]
	global_load_dwordx4 v[192:195], v[234:235], off
	global_load_dwordx4 v[196:199], v[234:235], off offset:256
	s_mov_b32 s98, 0x90000
	v_lshl_add_u64 v[236:237], v[144:145], 0, s[98:99]
	global_load_dwordx4 v[200:203], v[236:237], off offset:256
	global_load_dwordx4 v[204:207], v[236:237], off
	s_mov_b32 s98, 0xa0000
	v_lshl_add_u64 v[238:239], v[144:145], 0, s[98:99]
	global_load_dwordx4 v[212:215], v[238:239], off offset:256
	global_load_dwordx4 v[216:219], v[238:239], off
	s_mov_b32 s98, 0xb0000
	v_lshl_add_u64 v[240:241], v[144:145], 0, s[98:99]
	global_load_dwordx4 v[220:223], v[240:241], off offset:256
	global_load_dwordx4 v[224:227], v[240:241], off
	s_waitcnt vmcnt(14)
	v_lshlrev_b32_e32 v162, 16, v154
	v_and_b32_e32 v163, 0xffff0000, v154
	v_pk_fma_f32 v[162:163], v[128:129], s[14:15], v[162:163]
	v_lshlrev_b32_e32 v154, 16, v155
	v_cvt_pk_bf16_f32 v128, v162, v163
	v_fma_f32 v162, v162, v162, 0
	v_and_b32_e32 v155, 0xffff0000, v155
	v_fmac_f32_e32 v162, v163, v163
	v_pk_fma_f32 v[130:131], v[130:131], s[14:15], v[154:155]
	s_nop 0
	v_fmac_f32_e32 v162, v130, v130
	v_cvt_pk_bf16_f32 v129, v130, v131
	v_fmac_f32_e32 v162, v131, v131
	v_lshlrev_b32_e32 v130, 16, v156
	v_and_b32_e32 v131, 0xffff0000, v156
	v_pk_fma_f32 v[124:125], v[124:125], s[14:15], v[130:131]
	s_nop 0
	v_fmac_f32_e32 v162, v124, v124
	v_cvt_pk_bf16_f32 v130, v124, v125
	v_fmac_f32_e32 v162, v125, v125
	v_lshlrev_b32_e32 v124, 16, v157
	v_and_b32_e32 v125, 0xffff0000, v157
	v_pk_fma_f32 v[124:125], v[126:127], s[14:15], v[124:125]
	s_nop 0
	v_fmac_f32_e32 v162, v124, v124
	v_cvt_pk_bf16_f32 v131, v124, v125
	v_fmac_f32_e32 v162, v125, v125
	v_lshlrev_b32_e32 v124, 16, v158
	v_and_b32_e32 v125, 0xffff0000, v158
	v_pk_fma_f32 v[124:125], v[120:121], s[14:15], v[124:125]
	s_nop 0
	v_fmac_f32_e32 v162, v124, v124
	v_cvt_pk_bf16_f32 v120, v124, v125
	v_fmac_f32_e32 v162, v125, v125
	v_lshlrev_b32_e32 v124, 16, v159
	v_and_b32_e32 v125, 0xffff0000, v159
	v_pk_fma_f32 v[122:123], v[122:123], s[14:15], v[124:125]
	s_nop 0
	v_fmac_f32_e32 v162, v122, v122
	v_cvt_pk_bf16_f32 v121, v122, v123
	v_fmac_f32_e32 v162, v123, v123
	v_lshlrev_b32_e32 v122, 16, v160
	v_and_b32_e32 v123, 0xffff0000, v160
	v_pk_fma_f32 v[116:117], v[116:117], s[14:15], v[122:123]
	s_nop 0
	v_fmac_f32_e32 v162, v116, v116
	v_cvt_pk_bf16_f32 v122, v116, v117
	v_fmac_f32_e32 v162, v117, v117
	v_lshlrev_b32_e32 v116, 16, v161
	v_and_b32_e32 v117, 0xffff0000, v161
	v_pk_fma_f32 v[116:117], v[118:119], s[14:15], v[116:117]
	s_nop 0
	v_fmac_f32_e32 v162, v116, v116
	v_fmac_f32_e32 v162, v117, v117
	v_cvt_pk_bf16_f32 v123, v116, v117
	global_store_dwordx4 v2, v[128:131], s[2:3]
	global_store_dwordx4 v2, v[120:123], s[2:3] offset:256
	ds_bpermute_b32 v2, v153, v162
	s_mov_b32 s2, 0x10000
	v_add_co_u32_e32 v124, vcc, s2, v144
	s_mov_b32 s2, 0x20000
	s_waitcnt lgkmcnt(0)
	v_add_f32_e32 v2, v162, v2
	ds_bpermute_b32 v116, v152, v2
	v_addc_co_u32_e32 v125, vcc, 0, v145, vcc
	s_waitcnt lgkmcnt(0)
	v_add_f32_e32 v2, v2, v116
	s_waitcnt vmcnt(14)
	v_lshlrev_b32_e32 v126, 16, v172
	v_and_b32_e32 v127, 0xffff0000, v172
	v_pk_fma_f32 v[126:127], v[112:113], s[14:15], v[126:127]
	v_lshlrev_b32_e32 v120, 16, v173
	v_cvt_pk_bf16_f32 v112, v126, v127
	v_fma_f32 v126, v126, v126, 0
	v_and_b32_e32 v121, 0xffff0000, v173
	v_fmac_f32_e32 v126, v127, v127
	v_pk_fma_f32 v[114:115], v[114:115], s[14:15], v[120:121]
	s_nop 0
	v_fmac_f32_e32 v126, v114, v114
	v_cvt_pk_bf16_f32 v113, v114, v115
	v_fmac_f32_e32 v126, v115, v115
	v_lshlrev_b32_e32 v114, 16, v174
	v_and_b32_e32 v115, 0xffff0000, v174
	v_pk_fma_f32 v[108:109], v[108:109], s[14:15], v[114:115]
	s_nop 0
	v_fmac_f32_e32 v126, v108, v108
	v_cvt_pk_bf16_f32 v114, v108, v109
	v_fmac_f32_e32 v126, v109, v109
	v_lshlrev_b32_e32 v108, 16, v175
	v_and_b32_e32 v109, 0xffff0000, v175
	v_pk_fma_f32 v[108:109], v[110:111], s[14:15], v[108:109]
	v_add_co_u32_e32 v110, vcc, s2, v144
	v_fmac_f32_e32 v126, v108, v108
	v_cvt_pk_bf16_f32 v115, v108, v109
	v_fmac_f32_e32 v126, v109, v109
	v_lshlrev_b32_e32 v108, 16, v168
	v_and_b32_e32 v109, 0xffff0000, v168
	v_pk_fma_f32 v[108:109], v[104:105], s[14:15], v[108:109]
	v_addc_co_u32_e32 v111, vcc, 0, v145, vcc
	v_fmac_f32_e32 v126, v108, v108
	v_cvt_pk_bf16_f32 v104, v108, v109
	v_fmac_f32_e32 v126, v109, v109
	v_lshlrev_b32_e32 v108, 16, v169
	v_and_b32_e32 v109, 0xffff0000, v169
	v_pk_fma_f32 v[106:107], v[106:107], s[14:15], v[108:109]
	s_mov_b32 s2, 0x30000
	v_fmac_f32_e32 v126, v106, v106
	v_cvt_pk_bf16_f32 v105, v106, v107
	v_fmac_f32_e32 v126, v107, v107
	v_lshlrev_b32_e32 v106, 16, v170
	v_and_b32_e32 v107, 0xffff0000, v170
	v_pk_fma_f32 v[100:101], v[100:101], s[14:15], v[106:107]
	s_nop 0
	v_fmac_f32_e32 v126, v100, v100
	v_cvt_pk_bf16_f32 v106, v100, v101
	v_fmac_f32_e32 v126, v101, v101
	v_lshlrev_b32_e32 v100, 16, v171
	v_and_b32_e32 v101, 0xffff0000, v171
	v_pk_fma_f32 v[100:101], v[102:103], s[14:15], v[100:101]
	s_nop 0
	v_cvt_pk_bf16_f32 v107, v100, v101
	global_store_dwordx4 v[124:125], v[112:115], off
	global_store_dwordx4 v[124:125], v[104:107], off offset:256
	s_nop 0
	v_fmac_f32_e32 v126, v100, v100
	v_fmac_f32_e32 v126, v101, v101
	ds_bpermute_b32 v100, v153, v126
	s_waitcnt lgkmcnt(0)
	v_add_f32_e32 v100, v126, v100
	ds_bpermute_b32 v101, v152, v100
	s_waitcnt vmcnt(14)
	v_lshlrev_b32_e32 v112, 16, v180
	v_and_b32_e32 v113, 0xffff0000, v180
	v_pk_fma_f32 v[112:113], v[96:97], s[14:15], v[112:113]
	v_lshlrev_b32_e32 v106, 16, v181
	v_cvt_pk_bf16_f32 v96, v112, v113
	v_fma_f32 v112, v112, v112, 0
	v_and_b32_e32 v107, 0xffff0000, v181
	v_fmac_f32_e32 v112, v113, v113
	v_pk_fma_f32 v[98:99], v[98:99], s[14:15], v[106:107]
	s_nop 0
	v_fmac_f32_e32 v112, v98, v98
	v_cvt_pk_bf16_f32 v97, v98, v99
	v_fmac_f32_e32 v112, v99, v99
	v_lshlrev_b32_e32 v98, 16, v182
	v_and_b32_e32 v99, 0xffff0000, v182
	v_pk_fma_f32 v[92:93], v[92:93], s[14:15], v[98:99]
	s_nop 0
	v_fmac_f32_e32 v112, v92, v92
	v_cvt_pk_bf16_f32 v98, v92, v93
	v_fmac_f32_e32 v112, v93, v93
	v_lshlrev_b32_e32 v92, 16, v183
	v_and_b32_e32 v93, 0xffff0000, v183
	v_pk_fma_f32 v[92:93], v[94:95], s[14:15], v[92:93]
	s_nop 0
	v_fmac_f32_e32 v112, v92, v92
	v_cvt_pk_bf16_f32 v99, v92, v93
	v_fmac_f32_e32 v112, v93, v93
	v_lshlrev_b32_e32 v92, 16, v176
	v_and_b32_e32 v93, 0xffff0000, v176
	v_pk_fma_f32 v[92:93], v[88:89], s[14:15], v[92:93]
	s_nop 0
	v_fmac_f32_e32 v112, v92, v92
	v_cvt_pk_bf16_f32 v88, v92, v93
	v_fmac_f32_e32 v112, v93, v93
	v_lshlrev_b32_e32 v92, 16, v177
	v_and_b32_e32 v93, 0xffff0000, v177
	v_pk_fma_f32 v[90:91], v[90:91], s[14:15], v[92:93]
	v_add_co_u32_e32 v92, vcc, s2, v144
	v_fmac_f32_e32 v112, v90, v90
	v_cvt_pk_bf16_f32 v89, v90, v91
	v_fmac_f32_e32 v112, v91, v91
	v_lshlrev_b32_e32 v90, 16, v178
	v_and_b32_e32 v91, 0xffff0000, v178
	v_pk_fma_f32 v[84:85], v[84:85], s[14:15], v[90:91]
	v_addc_co_u32_e32 v93, vcc, 0, v145, vcc
	v_fmac_f32_e32 v112, v84, v84
	v_cvt_pk_bf16_f32 v90, v84, v85
	v_fmac_f32_e32 v112, v85, v85
	v_lshlrev_b32_e32 v84, 16, v179
	v_and_b32_e32 v85, 0xffff0000, v179
	v_pk_fma_f32 v[84:85], v[86:87], s[14:15], v[84:85]
	s_mov_b32 s2, 0x80000
	v_fmac_f32_e32 v112, v84, v84
	v_fmac_f32_e32 v112, v85, v85
	v_cvt_pk_bf16_f32 v91, v84, v85
	ds_bpermute_b32 v84, v153, v112
	global_store_dwordx4 v[110:111], v[96:99], off
	global_store_dwordx4 v[110:111], v[88:91], off offset:256
	s_waitcnt lgkmcnt(0)
	v_add_f32_e32 v94, v112, v84
	ds_bpermute_b32 v95, v152, v94
	s_waitcnt vmcnt(14)
	v_lshlrev_b32_e32 v96, 16, v188
	v_and_b32_e32 v97, 0xffff0000, v188
	v_pk_fma_f32 v[96:97], v[80:81], s[14:15], v[96:97]
	v_lshlrev_b32_e32 v88, 16, v189
	v_cvt_pk_bf16_f32 v80, v96, v97
	v_fma_f32 v96, v96, v96, 0
	v_and_b32_e32 v89, 0xffff0000, v189
	v_fmac_f32_e32 v96, v97, v97
	v_pk_fma_f32 v[82:83], v[82:83], s[14:15], v[88:89]
	s_nop 0
	v_fmac_f32_e32 v96, v82, v82
	v_cvt_pk_bf16_f32 v81, v82, v83
	v_fmac_f32_e32 v96, v83, v83
	v_lshlrev_b32_e32 v82, 16, v190
	v_and_b32_e32 v83, 0xffff0000, v190
	v_pk_fma_f32 v[76:77], v[76:77], s[14:15], v[82:83]
	s_nop 0
	v_fmac_f32_e32 v96, v76, v76
	v_cvt_pk_bf16_f32 v82, v76, v77
	v_fmac_f32_e32 v96, v77, v77
	v_lshlrev_b32_e32 v76, 16, v191
	v_and_b32_e32 v77, 0xffff0000, v191
	v_pk_fma_f32 v[76:77], v[78:79], s[14:15], v[76:77]
	v_add_co_u32_e32 v78, vcc, s2, v144
	v_fmac_f32_e32 v96, v76, v76
	v_cvt_pk_bf16_f32 v83, v76, v77
	v_fmac_f32_e32 v96, v77, v77
	v_lshlrev_b32_e32 v76, 16, v184
	v_and_b32_e32 v77, 0xffff0000, v184
	v_pk_fma_f32 v[76:77], v[72:73], s[14:15], v[76:77]
	v_addc_co_u32_e32 v79, vcc, 0, v145, vcc
	v_fmac_f32_e32 v96, v76, v76
	v_cvt_pk_bf16_f32 v72, v76, v77
	v_fmac_f32_e32 v96, v77, v77
	v_lshlrev_b32_e32 v76, 16, v185
	v_and_b32_e32 v77, 0xffff0000, v185
	v_pk_fma_f32 v[74:75], v[74:75], s[14:15], v[76:77]
	s_mov_b32 s2, 0x90000
	v_fmac_f32_e32 v96, v74, v74
	v_cvt_pk_bf16_f32 v73, v74, v75
	v_fmac_f32_e32 v96, v75, v75
	v_lshlrev_b32_e32 v74, 16, v186
	v_and_b32_e32 v75, 0xffff0000, v186
	v_pk_fma_f32 v[68:69], v[68:69], s[14:15], v[74:75]
	s_nop 0
	v_fmac_f32_e32 v96, v68, v68
	v_cvt_pk_bf16_f32 v74, v68, v69
	v_fmac_f32_e32 v96, v69, v69
	v_lshlrev_b32_e32 v68, 16, v187
	v_and_b32_e32 v69, 0xffff0000, v187
	v_pk_fma_f32 v[68:69], v[70:71], s[14:15], v[68:69]
	s_nop 0
	v_cvt_pk_bf16_f32 v75, v68, v69
	global_store_dwordx4 v[92:93], v[80:83], off
	global_store_dwordx4 v[92:93], v[72:75], off offset:256
	v_fmac_f32_e32 v96, v68, v68
	v_fmac_f32_e32 v96, v69, v69
	ds_bpermute_b32 v68, v153, v96
	s_waitcnt lgkmcnt(0)
	v_add_f32_e32 v68, v96, v68
	ds_bpermute_b32 v69, v152, v68
	s_waitcnt vmcnt(15)
	v_lshlrev_b32_e32 v80, 16, v192
	v_and_b32_e32 v81, 0xffff0000, v192
	v_pk_fma_f32 v[80:81], v[64:65], s[14:15], v[80:81]
	v_lshlrev_b32_e32 v70, 16, v193
	v_cvt_pk_bf16_f32 v64, v80, v81
	v_fma_f32 v80, v80, v80, 0
	v_and_b32_e32 v71, 0xffff0000, v193
	v_fmac_f32_e32 v80, v81, v81
	v_pk_fma_f32 v[66:67], v[66:67], s[14:15], v[70:71]
	s_nop 0
	v_fmac_f32_e32 v80, v66, v66
	v_cvt_pk_bf16_f32 v65, v66, v67
	v_fmac_f32_e32 v80, v67, v67
	v_lshlrev_b32_e32 v66, 16, v194
	v_and_b32_e32 v67, 0xffff0000, v194
	v_pk_fma_f32 v[60:61], v[60:61], s[14:15], v[66:67]
	s_nop 0
	v_fmac_f32_e32 v80, v60, v60
	v_cvt_pk_bf16_f32 v66, v60, v61
	v_fmac_f32_e32 v80, v61, v61
	v_lshlrev_b32_e32 v60, 16, v195
	v_and_b32_e32 v61, 0xffff0000, v195
	v_pk_fma_f32 v[60:61], v[62:63], s[14:15], v[60:61]
	v_add_co_u32_e32 v62, vcc, s2, v144
	v_fmac_f32_e32 v80, v60, v60
	v_cvt_pk_bf16_f32 v67, v60, v61
	v_fmac_f32_e32 v80, v61, v61
	s_waitcnt vmcnt(14)
	v_lshlrev_b32_e32 v60, 16, v196
	v_and_b32_e32 v61, 0xffff0000, v196
	v_pk_fma_f32 v[60:61], v[56:57], s[14:15], v[60:61]
	v_addc_co_u32_e32 v63, vcc, 0, v145, vcc
	v_fmac_f32_e32 v80, v60, v60
	v_cvt_pk_bf16_f32 v56, v60, v61
	v_fmac_f32_e32 v80, v61, v61
	v_lshlrev_b32_e32 v60, 16, v197
	v_and_b32_e32 v61, 0xffff0000, v197
	v_pk_fma_f32 v[58:59], v[58:59], s[14:15], v[60:61]
	s_mov_b32 s2, 0xa0000
	v_fmac_f32_e32 v80, v58, v58
	v_cvt_pk_bf16_f32 v57, v58, v59
	v_fmac_f32_e32 v80, v59, v59
	v_lshlrev_b32_e32 v58, 16, v198
	v_and_b32_e32 v59, 0xffff0000, v198
	v_pk_fma_f32 v[52:53], v[52:53], s[14:15], v[58:59]
	s_nop 0
	v_fmac_f32_e32 v80, v52, v52
	v_cvt_pk_bf16_f32 v58, v52, v53
	v_fmac_f32_e32 v80, v53, v53
	v_lshlrev_b32_e32 v52, 16, v199
	v_and_b32_e32 v53, 0xffff0000, v199
	v_pk_fma_f32 v[52:53], v[54:55], s[14:15], v[52:53]
	s_nop 0
	v_cvt_pk_bf16_f32 v59, v52, v53
	global_store_dwordx4 v[78:79], v[64:67], off
	global_store_dwordx4 v[78:79], v[56:59], off offset:256
	s_nop 0
	v_fmac_f32_e32 v80, v52, v52
	v_fmac_f32_e32 v80, v53, v53
	ds_bpermute_b32 v52, v153, v80
	s_waitcnt lgkmcnt(0)
	v_add_f32_e32 v52, v80, v52
	ds_bpermute_b32 v53, v152, v52
	s_waitcnt vmcnt(14)
	v_lshlrev_b32_e32 v64, 16, v204
	v_and_b32_e32 v65, 0xffff0000, v204
	v_pk_fma_f32 v[64:65], v[48:49], s[14:15], v[64:65]
	v_lshlrev_b32_e32 v58, 16, v205
	v_cvt_pk_bf16_f32 v48, v64, v65
	v_fma_f32 v64, v64, v64, 0
	v_and_b32_e32 v59, 0xffff0000, v205
	v_fmac_f32_e32 v64, v65, v65
	v_pk_fma_f32 v[50:51], v[50:51], s[14:15], v[58:59]
	s_nop 0
	v_fmac_f32_e32 v64, v50, v50
	v_cvt_pk_bf16_f32 v49, v50, v51
	v_fmac_f32_e32 v64, v51, v51
	v_lshlrev_b32_e32 v50, 16, v206
	v_and_b32_e32 v51, 0xffff0000, v206
	v_pk_fma_f32 v[44:45], v[44:45], s[14:15], v[50:51]
	s_nop 0
	v_fmac_f32_e32 v64, v44, v44
	v_cvt_pk_bf16_f32 v50, v44, v45
	v_fmac_f32_e32 v64, v45, v45
	v_lshlrev_b32_e32 v44, 16, v207
	v_and_b32_e32 v45, 0xffff0000, v207
	v_pk_fma_f32 v[44:45], v[46:47], s[14:15], v[44:45]
	v_add_co_u32_e32 v46, vcc, s2, v144
	v_fmac_f32_e32 v64, v44, v44
	v_cvt_pk_bf16_f32 v51, v44, v45
	v_fmac_f32_e32 v64, v45, v45
	v_lshlrev_b32_e32 v44, 16, v200
	v_and_b32_e32 v45, 0xffff0000, v200
	v_pk_fma_f32 v[44:45], v[40:41], s[14:15], v[44:45]
	v_addc_co_u32_e32 v47, vcc, 0, v145, vcc
	v_fmac_f32_e32 v64, v44, v44
	v_cvt_pk_bf16_f32 v40, v44, v45
	v_fmac_f32_e32 v64, v45, v45
	v_lshlrev_b32_e32 v44, 16, v201
	v_and_b32_e32 v45, 0xffff0000, v201
	v_pk_fma_f32 v[42:43], v[42:43], s[14:15], v[44:45]
	s_mov_b32 s2, 0xb0000
	v_fmac_f32_e32 v64, v42, v42
	v_cvt_pk_bf16_f32 v41, v42, v43
	v_fmac_f32_e32 v64, v43, v43
	v_lshlrev_b32_e32 v42, 16, v202
	v_and_b32_e32 v43, 0xffff0000, v202
	v_pk_fma_f32 v[36:37], v[36:37], s[14:15], v[42:43]
	s_nop 0
	v_fmac_f32_e32 v64, v36, v36
	v_cvt_pk_bf16_f32 v42, v36, v37
	v_fmac_f32_e32 v64, v37, v37
	v_lshlrev_b32_e32 v36, 16, v203
	v_and_b32_e32 v37, 0xffff0000, v203
	v_pk_fma_f32 v[36:37], v[38:39], s[14:15], v[36:37]
	s_nop 0
	v_cvt_pk_bf16_f32 v43, v36, v37
	global_store_dwordx4 v[62:63], v[48:51], off
	global_store_dwordx4 v[62:63], v[40:43], off offset:256
	s_nop 0
	v_fmac_f32_e32 v64, v36, v36
	v_fmac_f32_e32 v64, v37, v37
	ds_bpermute_b32 v36, v153, v64
	s_waitcnt lgkmcnt(0)
	v_add_f32_e32 v36, v64, v36
	ds_bpermute_b32 v37, v152, v36
	s_waitcnt vmcnt(14)
	v_lshlrev_b32_e32 v48, 16, v216
	v_and_b32_e32 v49, 0xffff0000, v216
	v_pk_fma_f32 v[48:49], v[32:33], s[14:15], v[48:49]
	v_lshlrev_b32_e32 v42, 16, v217
	v_cvt_pk_bf16_f32 v32, v48, v49
	v_fma_f32 v48, v48, v48, 0
	v_and_b32_e32 v43, 0xffff0000, v217
	v_fmac_f32_e32 v48, v49, v49
	v_pk_fma_f32 v[34:35], v[34:35], s[14:15], v[42:43]
	s_nop 0
	v_fmac_f32_e32 v48, v34, v34
	v_cvt_pk_bf16_f32 v33, v34, v35
	v_fmac_f32_e32 v48, v35, v35
	v_lshlrev_b32_e32 v34, 16, v218
	v_and_b32_e32 v35, 0xffff0000, v218
	v_pk_fma_f32 v[28:29], v[28:29], s[14:15], v[34:35]
	s_nop 0
	v_fmac_f32_e32 v48, v28, v28
	v_cvt_pk_bf16_f32 v34, v28, v29
	v_fmac_f32_e32 v48, v29, v29
	v_lshlrev_b32_e32 v28, 16, v219
	v_and_b32_e32 v29, 0xffff0000, v219
	v_pk_fma_f32 v[28:29], v[30:31], s[14:15], v[28:29]
	s_nop 0
	v_fmac_f32_e32 v48, v28, v28
	v_cvt_pk_bf16_f32 v35, v28, v29
	v_fmac_f32_e32 v48, v29, v29
	v_lshlrev_b32_e32 v28, 16, v212
	v_and_b32_e32 v29, 0xffff0000, v212
	v_pk_fma_f32 v[28:29], v[24:25], s[14:15], v[28:29]
	s_nop 0
	v_fmac_f32_e32 v48, v28, v28
	v_cvt_pk_bf16_f32 v24, v28, v29
	v_fmac_f32_e32 v48, v29, v29
	v_lshlrev_b32_e32 v28, 16, v213
	v_and_b32_e32 v29, 0xffff0000, v213
	v_pk_fma_f32 v[26:27], v[26:27], s[14:15], v[28:29]
	v_add_co_u32_e32 v28, vcc, s2, v144
	v_fmac_f32_e32 v48, v26, v26
	v_cvt_pk_bf16_f32 v25, v26, v27
	v_fmac_f32_e32 v48, v27, v27
	v_lshlrev_b32_e32 v26, 16, v214
	v_and_b32_e32 v27, 0xffff0000, v214
	v_pk_fma_f32 v[20:21], v[20:21], s[14:15], v[26:27]
	v_addc_co_u32_e32 v29, vcc, 0, v145, vcc
	v_fmac_f32_e32 v48, v20, v20
	v_cvt_pk_bf16_f32 v26, v20, v21
	v_fmac_f32_e32 v48, v21, v21
	v_lshlrev_b32_e32 v20, 16, v215
	v_and_b32_e32 v21, 0xffff0000, v215
	v_pk_fma_f32 v[20:21], v[22:23], s[14:15], v[20:21]
	s_nop 0
	v_fmac_f32_e32 v48, v20, v20
	v_fmac_f32_e32 v48, v21, v21
	v_cvt_pk_bf16_f32 v27, v20, v21
	ds_bpermute_b32 v20, v153, v48
	global_store_dwordx4 v[46:47], v[32:35], off
	global_store_dwordx4 v[46:47], v[24:27], off offset:256
	s_waitcnt lgkmcnt(0)
	v_add_f32_e32 v30, v48, v20
	ds_bpermute_b32 v31, v152, v30
	s_waitcnt vmcnt(14)
	v_lshlrev_b32_e32 v32, 16, v224
	v_and_b32_e32 v33, 0xffff0000, v224
	v_pk_fma_f32 v[32:33], v[16:17], s[14:15], v[32:33]
	v_lshlrev_b32_e32 v24, 16, v225
	v_cvt_pk_bf16_f32 v16, v32, v33
	v_fma_f32 v32, v32, v32, 0
	v_and_b32_e32 v25, 0xffff0000, v225
	v_fmac_f32_e32 v32, v33, v33
	v_pk_fma_f32 v[18:19], v[18:19], s[14:15], v[24:25]
	s_nop 0
	v_fmac_f32_e32 v32, v18, v18
	v_cvt_pk_bf16_f32 v17, v18, v19
	v_fmac_f32_e32 v32, v19, v19
	v_lshlrev_b32_e32 v18, 16, v226
	v_and_b32_e32 v19, 0xffff0000, v226
	v_pk_fma_f32 v[12:13], v[12:13], s[14:15], v[18:19]
	s_nop 0
	v_fmac_f32_e32 v32, v12, v12
	v_cvt_pk_bf16_f32 v18, v12, v13
	v_fmac_f32_e32 v32, v13, v13
	v_lshlrev_b32_e32 v12, 16, v227
	v_and_b32_e32 v13, 0xffff0000, v227
	v_pk_fma_f32 v[12:13], v[14:15], s[14:15], v[12:13]
	s_nop 0
	v_fmac_f32_e32 v32, v12, v12
	v_cvt_pk_bf16_f32 v19, v12, v13
	v_fmac_f32_e32 v32, v13, v13
	v_lshlrev_b32_e32 v12, 16, v220
	v_and_b32_e32 v13, 0xffff0000, v220
	v_pk_fma_f32 v[12:13], v[8:9], s[14:15], v[12:13]
	s_nop 0
	v_fmac_f32_e32 v32, v12, v12
	v_cvt_pk_bf16_f32 v8, v12, v13
	v_fmac_f32_e32 v32, v13, v13
	v_lshlrev_b32_e32 v12, 16, v221
	v_and_b32_e32 v13, 0xffff0000, v221
	v_pk_fma_f32 v[10:11], v[10:11], s[14:15], v[12:13]
	s_nop 0
	v_fmac_f32_e32 v32, v10, v10
	v_cvt_pk_bf16_f32 v9, v10, v11
	v_fmac_f32_e32 v32, v11, v11
	v_lshlrev_b32_e32 v10, 16, v222
	v_and_b32_e32 v11, 0xffff0000, v222
	v_pk_fma_f32 v[4:5], v[4:5], s[14:15], v[10:11]
	s_nop 0
	v_fmac_f32_e32 v32, v4, v4
	v_cvt_pk_bf16_f32 v10, v4, v5
	v_fmac_f32_e32 v32, v5, v5
	v_lshlrev_b32_e32 v4, 16, v223
	v_and_b32_e32 v5, 0xffff0000, v223
	v_pk_fma_f32 v[4:5], v[6:7], s[14:15], v[4:5]
	s_nop 0
	v_fmac_f32_e32 v32, v4, v4
	v_fmac_f32_e32 v32, v5, v5
	v_cvt_pk_bf16_f32 v11, v4, v5
	ds_bpermute_b32 v4, v153, v32
	global_store_dwordx4 v[28:29], v[16:19], off
	global_store_dwordx4 v[28:29], v[8:11], off offset:256
	s_waitcnt lgkmcnt(0)
	v_add_f32_e32 v4, v32, v4
	ds_bpermute_b32 v5, v152, v4
	s_and_saveexec_b64 s[2:3], s[38:39]
	v_add_f32_e32 v2, v30, v31
	v_add_f32_e32 v6, v52, v53
	v_add_f32_e32 v7, v94, v95
	v_cndmask_b32_e64 v2, v2, v6, s[42:43]
	v_cndmask_b32_e64 v2, v2, v7, s[40:41]
	s_or_b64 exec, exec, s[2:3]
	v_add_f32_e32 v8, v36, v37
	s_waitcnt lgkmcnt(0)
	v_add_f32_e32 v4, v4, v5
	v_add_f32_e32 v7, v68, v69
	v_cndmask_b32_e64 v4, v4, v8, s[42:43]
	v_add_f32_e32 v6, v100, v101
	v_cndmask_b32_e64 v4, v4, v7, s[40:41]
	v_cndmask_b32_e64 v6, v4, v6, s[36:37]
	v_add_u32_e32 v4, v148, v151
	v_ashrrev_i32_e32 v5, 31, v4
	v_readlane_b32 s2, v252, 45
	v_lshlrev_b64 v[4:5], 7, v[4:5]
	v_readlane_b32 s3, v252, 46
	s_and_b64 vcc, exec, s[44:45]
	s_nop 0
	v_lshl_add_u64 v[4:5], s[2:3], 0, v[4:5]
	s_lshl_b32 s2, s17, 2
	s_ashr_i32 s3, s2, 31
	v_lshl_add_u64 v[4:5], s[2:3], 2, v[4:5]
	v_readlane_b32 s2, v255, 9
	v_readlane_b32 s3, v255, 10
	s_nop 1
	v_lshl_add_u64 v[4:5], v[4:5], 0, s[2:3]
	s_mov_b64 s[2:3], -1
	global_store_dword v[4:5], v2, off
	global_store_dword v[4:5], v6, off offset:2048
	s_cbranch_vccnz .LBB0_820
	s_andn2_b64 vcc, exec, s[12:13]
	s_cbranch_vccnz .LBB0_819
	s_barrier
	s_branch .LBB0_819

.LBB0_968:
	s_or_b64 exec, exec, s[0:1]
	v_readlane_b32 s12, v252, 5
	v_readlane_b32 s26, v252, 19
	v_readlane_b32 s27, v252, 20
	s_waitcnt vmcnt(0)
	ds_bpermute_b32 v48, v38, v45
	s_add_i32 s2, s2, s28
	v_lshl_add_u64 v[46:47], s[26:27], 0, v[36:37]
	v_add_co_u32_e64 v50, s[0:1], s3, v46
	s_waitcnt lgkmcnt(0)
	v_add_f32_e32 v45, v45, v48
	v_addc_co_u32_e64 v51, s[0:1], 0, v47, s[0:1]
	global_load_dwordx2 v[46:47], v[50:51], off
	global_load_dwordx2 v[60:61], v[50:51], off offset:512
	global_load_dwordx2 v[62:63], v[50:51], off offset:1024
	global_load_dwordx2 v[64:65], v[50:51], off offset:1536
	global_load_dwordx2 v[66:67], v[50:51], off offset:2048
	global_load_dwordx2 v[68:69], v[50:51], off offset:2560
	global_load_dwordx2 v[70:71], v[50:51], off offset:3072
	global_load_dwordx2 v[72:73], v[50:51], off offset:3584
	ds_bpermute_b32 v48, v39, v45
	v_lshl_add_u64 v[32:33], v[32:33], 0, s[4:5]
	s_cmpk_lt_i32 s2, 0x2000
	v_lshl_add_u64 v[36:37], v[36:37], 0, s[8:9]
	v_readlane_b32 s13, v252, 6
	s_waitcnt lgkmcnt(0)
	v_add_f32_e32 v45, v45, v48
	ds_bpermute_b32 v48, v40, v45
	v_readlane_b32 s14, v252, 7
	v_readlane_b32 s15, v252, 8
	v_readlane_b32 s16, v252, 9
	v_readlane_b32 s17, v252, 10
	s_waitcnt lgkmcnt(0)
	v_add_f32_e32 v45, v45, v48
	ds_bpermute_b32 v48, v41, v45
	v_readlane_b32 s18, v252, 11
	v_readlane_b32 s19, v252, 12
	v_readlane_b32 s20, v252, 13
	v_readlane_b32 s21, v252, 14
	s_waitcnt lgkmcnt(0)
	v_add_f32_e32 v45, v45, v48
	ds_bpermute_b32 v48, v42, v45
	v_readlane_b32 s22, v252, 15
	v_readlane_b32 s23, v252, 16
	v_readlane_b32 s24, v252, 17
	v_readlane_b32 s25, v252, 18
	s_waitcnt lgkmcnt(0)
	v_add_f32_e32 v45, v45, v48
	ds_bpermute_b32 v48, v43, v45
	s_waitcnt lgkmcnt(0)
	v_add_f32_e32 v45, v45, v48
	v_fmamk_f32 v45, v45, 0x3a000000, v44
	v_rsq_f32_e32 v52, v45
	s_waitcnt vmcnt(7)
	v_lshlrev_b32_e32 v48, 16, v46
	v_and_b32_e32 v49, 0xffff0000, v46
	v_lshlrev_b32_e32 v46, 16, v47
	v_and_b32_e32 v47, 0xffff0000, v47
	v_pk_mul_f32 v[54:55], v[52:53], v[48:49] op_sel_hi:[0,1]
	v_pk_mul_f32 v[46:47], v[52:53], v[46:47] op_sel_hi:[0,1]
	v_pk_mul_f32 v[48:49], v[2:3], v[46:47]
	v_pk_mul_f32 v[46:47], v[0:1], v[54:55]
	global_store_dwordx4 v[34:35], v[46:49], off offset:-4096
	s_nop 1
	s_waitcnt vmcnt(7)
	v_lshlrev_b32_e32 v48, 16, v60
	v_and_b32_e32 v49, 0xffff0000, v60
	v_lshlrev_b32_e32 v46, 16, v61
	v_and_b32_e32 v47, 0xffff0000, v61
	v_pk_mul_f32 v[54:55], v[52:53], v[48:49] op_sel_hi:[0, 1]
	v_pk_mul_f32 v[46:47], v[52:53], v[46:47] op_sel_hi:[0, 1]
	v_pk_mul_f32 v[48:49], v[6:7], v[46:47]
	v_pk_mul_f32 v[46:47], v[4:5], v[54:55]
	global_store_dwordx4 v[34:35], v[46:49], off offset:-3072
	s_nop 1
	s_waitcnt vmcnt(7)
	v_lshlrev_b32_e32 v48, 16, v62
	v_and_b32_e32 v49, 0xffff0000, v62
	v_lshlrev_b32_e32 v46, 16, v63
	v_and_b32_e32 v47, 0xffff0000, v63
	v_pk_mul_f32 v[54:55], v[52:53], v[48:49] op_sel_hi:[0, 1]
	v_pk_mul_f32 v[46:47], v[52:53], v[46:47] op_sel_hi:[0, 1]
	v_pk_mul_f32 v[48:49], v[10:11], v[46:47]
	v_pk_mul_f32 v[46:47], v[8:9], v[54:55]
	global_store_dwordx4 v[34:35], v[46:49], off offset:-2048
	s_nop 1
	s_waitcnt vmcnt(7)
	v_lshlrev_b32_e32 v48, 16, v64
	v_and_b32_e32 v49, 0xffff0000, v64
	v_lshlrev_b32_e32 v46, 16, v65
	v_and_b32_e32 v47, 0xffff0000, v65
	v_pk_mul_f32 v[54:55], v[52:53], v[48:49] op_sel_hi:[0, 1]
	v_pk_mul_f32 v[46:47], v[52:53], v[46:47] op_sel_hi:[0, 1]
	v_pk_mul_f32 v[48:49], v[14:15], v[46:47]
	v_pk_mul_f32 v[46:47], v[12:13], v[54:55]
	global_store_dwordx4 v[34:35], v[46:49], off offset:-1024
	s_nop 1
	s_waitcnt vmcnt(7)
	v_lshlrev_b32_e32 v48, 16, v66
	v_and_b32_e32 v49, 0xffff0000, v66
	v_lshlrev_b32_e32 v46, 16, v67
	v_and_b32_e32 v47, 0xffff0000, v67
	v_pk_mul_f32 v[54:55], v[52:53], v[48:49] op_sel_hi:[0, 1]
	v_pk_mul_f32 v[46:47], v[52:53], v[46:47] op_sel_hi:[0, 1]
	v_pk_mul_f32 v[48:49], v[18:19], v[46:47]
	v_pk_mul_f32 v[46:47], v[16:17], v[54:55]
	global_store_dwordx4 v[34:35], v[46:49], off
	s_nop 1
	s_waitcnt vmcnt(7)
	v_lshlrev_b32_e32 v48, 16, v68
	v_and_b32_e32 v49, 0xffff0000, v68
	v_lshlrev_b32_e32 v46, 16, v69
	v_and_b32_e32 v47, 0xffff0000, v69
	v_pk_mul_f32 v[54:55], v[52:53], v[48:49] op_sel_hi:[0, 1]
	v_pk_mul_f32 v[46:47], v[52:53], v[46:47] op_sel_hi:[0, 1]
	v_pk_mul_f32 v[48:49], v[22:23], v[46:47]
	v_pk_mul_f32 v[46:47], v[20:21], v[54:55]
	global_store_dwordx4 v[34:35], v[46:49], off offset:1024
	s_nop 1
	s_waitcnt vmcnt(7)
	v_lshlrev_b32_e32 v48, 16, v70
	v_and_b32_e32 v49, 0xffff0000, v70
	v_lshlrev_b32_e32 v46, 16, v71
	v_and_b32_e32 v47, 0xffff0000, v71
	v_pk_mul_f32 v[54:55], v[52:53], v[48:49] op_sel_hi:[0, 1]
	v_pk_mul_f32 v[46:47], v[52:53], v[46:47] op_sel_hi:[0, 1]
	v_pk_mul_f32 v[48:49], v[26:27], v[46:47]
	v_pk_mul_f32 v[46:47], v[24:25], v[54:55]
	global_store_dwordx4 v[34:35], v[46:49], off offset:2048
	s_nop 1
	s_waitcnt vmcnt(7)
	v_lshlrev_b32_e32 v48, 16, v72
	v_and_b32_e32 v49, 0xffff0000, v72
	v_lshlrev_b32_e32 v46, 16, v73
	v_and_b32_e32 v47, 0xffff0000, v73
	v_pk_mul_f32 v[50:51], v[52:53], v[48:49] op_sel_hi:[0, 1]
	v_pk_mul_f32 v[46:47], v[52:53], v[46:47] op_sel_hi:[0, 1]
	v_pk_mul_f32 v[48:49], v[30:31], v[46:47]
	v_pk_mul_f32 v[46:47], v[28:29], v[50:51]
	global_store_dwordx4 v[34:35], v[46:49], off offset:3072
	v_lshl_add_u64 v[34:35], v[34:35], 0, s[6:7]
	s_cbranch_scc0 .LBB0_971

	.amdhsa_kernel _Z8mega_fwd4Args
		.amdhsa_group_segment_fixed_size 0
		.amdhsa_private_segment_fixed_size 0
		.amdhsa_kernarg_size 392
		.amdhsa_user_sgpr_count 2
		.amdhsa_user_sgpr_dispatch_ptr 0
		.amdhsa_user_sgpr_queue_ptr 0
		.amdhsa_user_sgpr_kernarg_segment_ptr 1
		.amdhsa_user_sgpr_dispatch_id 0
		.amdhsa_user_sgpr_kernarg_preload_length 0
		.amdhsa_user_sgpr_kernarg_preload_offset 0
		.amdhsa_user_sgpr_private_segment_size 0
		.amdhsa_uses_dynamic_stack 0
		.amdhsa_enable_private_segment 0
		.amdhsa_system_sgpr_workgroup_id_x 1
		.amdhsa_system_sgpr_workgroup_id_y 0
		.amdhsa_system_sgpr_workgroup_id_z 0
		.amdhsa_system_sgpr_workgroup_info 0
		.amdhsa_system_vgpr_workitem_id 0
		.amdhsa_next_free_vgpr 256
		.amdhsa_next_free_sgpr 102
		.amdhsa_accum_offset 256
		.amdhsa_reserve_vcc 1
		.amdhsa_float_round_mode_32 0
		.amdhsa_float_round_mode_16_64 0
		.amdhsa_float_denorm_mode_32 3
		.amdhsa_float_denorm_mode_16_64 3
		.amdhsa_dx10_clamp 1
		.amdhsa_ieee_mode 1
		.amdhsa_fp16_overflow 0
		.amdhsa_tg_split 0
		.amdhsa_exception_fp_ieee_invalid_op 0
		.amdhsa_exception_fp_denorm_src 0
		.amdhsa_exception_fp_ieee_div_zero 0
		.amdhsa_exception_fp_ieee_overflow 0
		.amdhsa_exception_fp_ieee_underflow 0
		.amdhsa_exception_fp_ieee_inexact 0
		.amdhsa_exception_int_div_zero 0
	.end_amdhsa_kernel

amdhsa.kernels:
  - .agpr_count:     0
    .args:
      - .offset:         0
        .size:           136
        .value_kind:     by_value
      - .offset:         136
        .size:           4
        .value_kind:     hidden_block_count_x
      - .offset:         140
        .size:           4
        .value_kind:     hidden_block_count_y
      - .offset:         144
        .size:           4
        .value_kind:     hidden_block_count_z
      - .offset:         148
        .size:           2
        .value_kind:     hidden_group_size_x
      - .offset:         150
        .size:           2
        .value_kind:     hidden_group_size_y
      - .offset:         152
        .size:           2
        .value_kind:     hidden_group_size_z
      - .offset:         154
        .size:           2
        .value_kind:     hidden_remainder_x
      - .offset:         156
        .size:           2
        .value_kind:     hidden_remainder_y
      - .offset:         158
        .size:           2
        .value_kind:     hidden_remainder_z
      - .offset:         176
        .size:           8
        .value_kind:     hidden_global_offset_x
      - .offset:         184
        .size:           8
        .value_kind:     hidden_global_offset_y
      - .offset:         192
        .size:           8
        .value_kind:     hidden_global_offset_z
      - .offset:         200
        .size:           2
        .value_kind:     hidden_grid_dims
      - .offset:         256
        .size:           4
        .value_kind:     hidden_dynamic_lds_size
    .group_segment_fixed_size: 0
    .kernarg_segment_align: 8
    .kernarg_segment_size: 392
    .language:       OpenCL C
    .language_version:
      - 2
      - 0
    .max_flat_workgroup_size: 512
    .name:           _Z8mega_fwd4Args
    .private_segment_fixed_size: 0
    .sgpr_count:     108
    .sgpr_spill_count: 271
    .symbol:         _Z8mega_fwd4Args.kd
    .uniform_work_group_size: 1
    .uses_dynamic_stack: false
    .vgpr_count:     256
    .vgpr_spill_count: 0
    .wavefront_size: 64
